# p->bf16 conversion moved out of the memory-bound prep phase into the HGRN scan: idle consumer wave 7 converts 2 rows per scan step (software-pipelined loads)
# speedup vs baseline: 1.0180x; 1.0098x over previous
.LBB0_8:
	s_or_b64 exec, exec, s[6:7]
	s_lshl_b32 s0, s82, 9
	v_lshl_or_b32 v10, s86, 9, v0
	s_add_u32 s16, s80, 0x36000000
	s_mov_b32 s1, 0x90000
	s_addc_u32 s17, s81, 0
	v_cmp_gt_i32_e32 vcc, s1, v10
	s_and_saveexec_b64 s[6:7], vcc
	s_cbranch_execz .LBB0_30
	s_cmp_lg_u64 s[56:57], 0
	s_cbranch_scc1 .Lmy_w1_fast
	s_cselect_b64 s[2:3], -1, 0
	v_cndmask_b32_e64 v1, 0, 1, s[2:3]
	s_mov_b64 s[18:19], 0
	s_mov_b32 s1, 0x38e38e39
	v_cmp_ne_u32_e64 s[4:5], 1, v1
	s_mov_b32 s2, 0x8ffff
	v_mov_b32_e32 v9, v10
	s_branch .LBB0_14

.LBB0_384:
	s_or_b64 exec, exec, s[68:69]
	s_lshr_b32 s75, s74, 6
	s_cmpk_gt_u32 s74, 0xff
	s_mov_b64 s[0:1], -1
	s_cbranch_scc0 .LBB0_396
	s_setprio 1
	s_and_b32 s0, s94, 15
	s_lshl_b32 s72, s0, 22
	s_add_i32 s73, s75, -4
	s_cmp_lg_u32 s73, 0
	s_cselect_b64 s[0:1], -1, 0
	s_cmpk_lt_u32 s74, 0x1c0
	s_cselect_b64 s[68:69], -1, 0
	s_not_b32 s70, s75
	s_lshl_b32 s70, s70, 5
	s_and_b32 s87, s70, 32
	s_add_i32 s70, s75, -5
	v_or_b32_e32 v2, s87, v83
	s_cmp_lt_u32 s70, 2
	v_mul_u32_u24_e32 v3, 0x110, v2
	s_cselect_b64 s[70:71], -1, 0
	v_mul_u32_u24_e32 v105, 0x50, v2
	v_lshl_add_u32 v106, s73, 7, v90
	v_lshl_or_b32 v2, s73, 5, v83
	v_lshl_add_u32 v108, s73, 6, v91
	s_add_i32 s73, s87, s95
	s_waitcnt lgkmcnt(0)
	s_barrier
	s_add_i32 s73, s73, s86
	s_waitcnt lgkmcnt(0)
	s_barrier
	s_movk_i32 s88, 0x50
	s_lshl_b32 s73, s73, 1
	v_mul_lo_u32 v107, v2, s88
	s_or_b32 s72, s72, s73
	s_mov_b32 s73, s96
	v_mov_b32_e32 v2, 0
	s_mov_b32 s87, 1
	v_lshl_add_u64 v[80:81], v[78:79], 0, s[72:73]
	v_add_u32_e32 v109, v86, v3
	v_mov_b32_e32 v3, v2
	v_mov_b32_e32 v4, v2
	v_mov_b32_e32 v5, v2
	s_waitcnt vmcnt(0)
	v_mov_b32_e32 v6, v2
	v_mov_b32_e32 v7, v2
	v_mov_b32_e32 v8, v2
	v_mov_b32_e32 v9, v2
	v_mov_b32_e32 v10, v2
	v_mov_b32_e32 v11, v2
	v_mov_b32_e32 v12, v2
	v_mov_b32_e32 v13, v2
	v_mov_b32_e32 v14, v2
	v_mov_b32_e32 v15, v2
	v_mov_b32_e32 v16, v2
	v_mov_b32_e32 v17, v2
	v_mov_b32_e32 v18, v2
	v_mov_b32_e32 v19, v2
	v_mov_b32_e32 v20, v2
	v_mov_b32_e32 v21, v2
	v_mov_b32_e32 v22, v2
	v_mov_b32_e32 v23, v2
	v_mov_b32_e32 v24, v2
	v_mov_b32_e32 v25, v2
	v_mov_b32_e32 v26, v2
	v_mov_b32_e32 v27, v2
	v_mov_b32_e32 v28, v2
	v_mov_b32_e32 v29, v2
	v_mov_b32_e32 v30, v2
	v_mov_b32_e32 v31, v2
	v_mov_b32_e32 v32, v2
	v_mov_b32_e32 v33, v2
	s_and_b64 vcc, exec, s[68:69]
	s_cbranch_vccnz .Lmy_pc0_nosetup
	v_readlane_b32 s98, v255, 3
	v_readlane_b32 s99, v255, 4
	v_readlane_b32 s100, v255, 17
	s_nop 3
	s_lshl_b32 s101, s100, 18
	s_add_u32 s98, s98, s101
	s_addc_u32 s99, s99, 0
	v_lshlrev_b32_e32 v232, 4, v158
	v_mov_b32_e32 v233, 0
	v_lshl_add_u64 v[232:233], s[98:99], 0, v[232:233]
	s_lshl_b32 s101, s100, 17
	s_add_u32 s98, s80, s101
	s_addc_u32 s99, s81, 0
	s_add_u32 s98, s98, 0x34000000
	s_addc_u32 s99, s99, 0
	v_lshlrev_b32_e32 v234, 3, v158
	v_mov_b32_e32 v235, 0
	v_lshl_add_u64 v[234:235], s[98:99], 0, v[234:235]
	s_mov_b32 s98, 0x800
	s_mov_b32 s99, 0
	s_mov_b32 s100, 0x400
	s_mov_b32 s101, 0
	global_load_dwordx4 v[224:227], v[232:233], off
	global_load_dwordx4 v[228:231], v[232:233], off offset:1024
	v_lshl_add_u64 v[232:233], v[232:233], 0, s[98:99]
.Lmy_pc0_nosetup:
	s_branch .LBB0_387
.LBB0_386:
	s_nop 7
	v_lshl_add_u32 v46, s89, 9, v106
	ds_read_b128 v[34:37], v46
	ds_read_b128 v[38:41], v46 offset:32
	ds_read_b128 v[42:45], v46 offset:64
	ds_read_b128 v[46:49], v46 offset:96
	s_movk_i32 s72, 0x8000
	s_waitcnt lgkmcnt(3)
	v_pk_mul_f32 v[18:19], v[18:19], v[34:35]
	v_pk_mul_f32 v[2:3], v[2:3], v[34:35]
	v_lshlrev_b32_e32 v34, 1, v85
	s_waitcnt lgkmcnt(2)
	v_pk_mul_f32 v[22:23], v[22:23], v[38:39]
	v_pk_mul_f32 v[6:7], v[6:7], v[38:39]
	v_add3_u32 v38, s88, v107, v34
	s_waitcnt lgkmcnt(0)
	v_pk_mul_f32 v[32:33], v[32:33], v[48:49]
	v_pk_mul_f32 v[28:29], v[28:29], v[44:45]
	v_pk_mul_f32 v[24:25], v[24:25], v[40:41]
	v_pk_mul_f32 v[20:21], v[20:21], v[36:37]
	v_pk_mul_f32 v[30:31], v[30:31], v[46:47]
	v_pk_mul_f32 v[26:27], v[26:27], v[42:43]
	v_pk_mul_f32 v[16:17], v[16:17], v[48:49]
	v_pk_mul_f32 v[12:13], v[12:13], v[44:45]
	v_pk_mul_f32 v[8:9], v[8:9], v[40:41]
	v_pk_mul_f32 v[4:5], v[4:5], v[36:37]
	v_pk_mul_f32 v[14:15], v[14:15], v[46:47]
	v_pk_mul_f32 v[10:11], v[10:11], v[42:43]
	v_add3_u32 v50, s88, v88, v34
	ds_read_b128 v[34:37], v38 offset:26112
	ds_read_b128 v[38:41], v38 offset:26144
	ds_read_b128 v[42:45], v50 offset:36352
	ds_read_b128 v[46:49], v50 offset:36384
	s_waitcnt lgkmcnt(1)
	v_mfma_f32_32x32x16_bf16 v[18:33], v[34:37], v[42:45], v[18:33]
	ds_read_b128 v[42:45], v50 offset:38912
	s_add_i32 s87, s87, 1
	s_mov_b32 s73, -1
	v_lshl_add_u64 v[80:81], v[80:81], 0, s[72:73]
	s_cmpk_lg_i32 s87, 0x81
	s_waitcnt lgkmcnt(0)
	v_mfma_f32_32x32x16_bf16 v[2:17], v[34:37], v[42:45], v[2:17]
	ds_read_b128 v[34:37], v50 offset:38944
	v_add_u32_e32 v42, 0x2000, v108
	v_mfma_f32_32x32x16_bf16 v[18:33], v[38:41], v[46:49], v[18:33]
	s_waitcnt lgkmcnt(0)
	v_mfma_f32_32x32x16_bf16 v[2:17], v[38:41], v[34:37], v[2:17]
	s_nop 9
	v_cvt_pk_bf16_f32 v34, v18, v19
	v_cvt_pk_bf16_f32 v35, v20, v21
	v_cvt_pk_bf16_f32 v38, v22, v23
	v_cvt_pk_bf16_f32 v39, v24, v25
	ds_write2_b64 v108, v[34:35], v[38:39] offset1:2
	v_cvt_pk_bf16_f32 v34, v26, v27
	v_cvt_pk_bf16_f32 v35, v28, v29
	v_cvt_pk_bf16_f32 v36, v2, v3
	v_cvt_pk_bf16_f32 v37, v4, v5
	v_cvt_pk_bf16_f32 v40, v6, v7
	v_cvt_pk_bf16_f32 v41, v8, v9
	v_cvt_pk_bf16_f32 v38, v30, v31
	v_cvt_pk_bf16_f32 v39, v32, v33
	ds_write2_b64 v42, v[36:37], v[40:41] offset0:64 offset1:66
	v_cvt_pk_bf16_f32 v36, v10, v11
	v_cvt_pk_bf16_f32 v37, v12, v13
	v_cvt_pk_bf16_f32 v40, v14, v15
	v_cvt_pk_bf16_f32 v41, v16, v17
	ds_write2_b64 v108, v[34:35], v[38:39] offset0:4 offset1:6
	ds_write2_b64 v42, v[36:37], v[40:41] offset0:68 offset1:70
	s_waitcnt lgkmcnt(0)
	s_barrier
	s_cbranch_scc0 .LBB0_395

.Lmy_pc0:
	s_waitcnt vmcnt(0)
	v_cvt_pk_bf16_f32 v240, v224, v225
	v_cvt_pk_bf16_f32 v241, v226, v227
	v_cvt_pk_bf16_f32 v242, v228, v229
	v_cvt_pk_bf16_f32 v243, v230, v231
	global_store_dwordx2 v[234:235], v[240:241], off
	global_store_dwordx2 v[234:235], v[242:243], off offset:512
	v_lshl_add_u64 v[234:235], v[234:235], 0, s[100:101]
	s_cmpk_eq_i32 s87, 0x80
	s_cbranch_scc1 .LBB0_392
	global_load_dwordx4 v[224:227], v[232:233], off
	global_load_dwordx4 v[228:231], v[232:233], off offset:1024
	v_lshl_add_u64 v[232:233], v[232:233], 0, s[98:99]
	s_branch .LBB0_392

.LBB0_415:
	s_or_b64 exec, exec, s[68:69]
	v_readfirstlane_b32 s88, v0
	s_lshl_b32 s0, s94, 12
	s_lshr_b32 s87, s88, 6
	s_cmpk_gt_u32 s88, 0xff
	s_mov_b64 s[68:69], -1
	s_cbranch_scc0 .LBB0_427
	s_setprio 1
	s_mov_b32 s1, s96
	s_lshl_b64 s[74:75], s[0:1], 10
	s_add_i32 s92, s87, -4
	s_cmp_lg_u32 s92, 0
	s_cselect_b64 s[68:69], -1, 0
	s_cmpk_lt_u32 s88, 0x1c0
	s_cselect_b64 s[70:71], -1, 0
	s_not_b32 s72, s87
	s_lshl_b32 s72, s72, 5
	s_and_b32 s93, s72, 32
	s_add_i32 s72, s87, -5
	v_or_b32_e32 v2, s93, v83
	s_cmp_lt_u32 s72, 2
	v_mul_u32_u24_e32 v3, 0x110, v2
	s_cselect_b64 s[72:73], -1, 0
	v_mul_u32_u24_e32 v105, 0x50, v2
	v_lshl_add_u32 v106, s92, 7, v90
	v_lshl_or_b32 v2, s92, 5, v83
	v_lshl_add_u32 v108, s92, 6, v91
	s_add_i32 s92, s93, s95
	s_add_i32 s92, s92, s86
	s_waitcnt lgkmcnt(0)
	s_barrier
	s_lshl_b32 s86, s92, 1
	s_waitcnt lgkmcnt(0)
	s_barrier
	s_movk_i32 vcc_lo, 0x50
	s_add_u32 s74, s74, s86
	v_mul_lo_u32 v107, v2, vcc_lo
	s_addc_u32 s75, s75, 0
	v_mov_b32_e32 v2, 0
	s_mov_b32 s1, 0
	v_lshl_add_u64 v[80:81], v[76:77], 0, s[74:75]
	s_mov_b64 s[74:75], 0
	v_add_u32_e32 v109, v86, v3
	v_mov_b32_e32 v3, v2
	v_mov_b32_e32 v4, v2
	v_mov_b32_e32 v5, v2
	s_waitcnt vmcnt(0)
	v_mov_b32_e32 v6, v2
	v_mov_b32_e32 v7, v2
	v_mov_b32_e32 v8, v2
	v_mov_b32_e32 v9, v2
	v_mov_b32_e32 v10, v2
	v_mov_b32_e32 v11, v2
	v_mov_b32_e32 v12, v2
	v_mov_b32_e32 v13, v2
	v_mov_b32_e32 v14, v2
	v_mov_b32_e32 v15, v2
	v_mov_b32_e32 v16, v2
	v_mov_b32_e32 v17, v2
	v_mov_b32_e32 v18, v2
	v_mov_b32_e32 v19, v2
	v_mov_b32_e32 v20, v2
	v_mov_b32_e32 v21, v2
	v_mov_b32_e32 v22, v2
	v_mov_b32_e32 v23, v2
	v_mov_b32_e32 v24, v2
	v_mov_b32_e32 v25, v2
	v_mov_b32_e32 v26, v2
	v_mov_b32_e32 v27, v2
	v_mov_b32_e32 v28, v2
	v_mov_b32_e32 v29, v2
	v_mov_b32_e32 v30, v2
	v_mov_b32_e32 v31, v2
	v_mov_b32_e32 v32, v2
	v_mov_b32_e32 v33, v2
	s_and_b64 vcc, exec, s[70:71]
	s_cbranch_vccnz .Lmy_pc1_nosetup
	v_readlane_b32 s98, v255, 3
	v_readlane_b32 s99, v255, 4
	v_readlane_b32 s100, v255, 17
	s_nop 3
	s_lshl_b32 s101, s100, 18
	s_add_u32 s98, s98, s101
	s_addc_u32 s99, s99, 0
	v_lshlrev_b32_e32 v232, 4, v158
	v_mov_b32_e32 v233, 0
	v_lshl_add_u64 v[232:233], s[98:99], 0, v[232:233]
	s_lshl_b32 s101, s100, 17
	s_add_u32 s98, s80, s101
	s_addc_u32 s99, s81, 0
	s_add_u32 s98, s98, 0x34000000
	s_addc_u32 s99, s99, 0
	v_lshlrev_b32_e32 v234, 3, v158
	v_mov_b32_e32 v235, 0
	v_lshl_add_u64 v[234:235], s[98:99], 0, v[234:235]
	s_mov_b32 s98, 0x800
	s_mov_b32 s99, 0
	s_mov_b32 s100, 0x400
	s_mov_b32 s101, 0
	global_load_dwordx4 v[224:227], v[232:233], off
	global_load_dwordx4 v[228:231], v[232:233], off offset:1024
	v_lshl_add_u64 v[232:233], v[232:233], 0, s[98:99]
.Lmy_pc1_nosetup:
	s_branch .LBB0_418
.LBB0_417:
	s_nop 6
	v_lshl_add_u32 v46, s95, 9, v106
	ds_read_b128 v[34:37], v46
	ds_read_b128 v[38:41], v46 offset:32
	ds_read_b128 v[42:45], v46 offset:64
	ds_read_b128 v[46:49], v46 offset:96
	v_add3_u32 v50, s86, v88, v110
	s_waitcnt lgkmcnt(3)
	v_pk_mul_f32 v[20:21], v[20:21], v[36:37]
	s_waitcnt lgkmcnt(2)
	v_pk_mul_f32 v[22:23], v[22:23], v[38:39]
	v_pk_mul_f32 v[6:7], v[6:7], v[38:39]
	v_add3_u32 v38, s86, v107, v110
	s_waitcnt lgkmcnt(0)
	v_pk_mul_f32 v[32:33], v[32:33], v[48:49]
	v_pk_mul_f32 v[28:29], v[28:29], v[44:45]
	v_pk_mul_f32 v[24:25], v[24:25], v[40:41]
	v_pk_mul_f32 v[30:31], v[30:31], v[46:47]
	v_pk_mul_f32 v[26:27], v[26:27], v[42:43]
	v_pk_mul_f32 v[18:19], v[18:19], v[34:35]
	v_pk_mul_f32 v[16:17], v[16:17], v[48:49]
	v_pk_mul_f32 v[12:13], v[12:13], v[44:45]
	v_pk_mul_f32 v[8:9], v[8:9], v[40:41]
	v_pk_mul_f32 v[4:5], v[4:5], v[36:37]
	v_pk_mul_f32 v[14:15], v[14:15], v[46:47]
	v_pk_mul_f32 v[10:11], v[10:11], v[42:43]
	v_pk_mul_f32 v[2:3], v[2:3], v[34:35]
	ds_read_b128 v[34:37], v38 offset:26112
	ds_read_b128 v[38:41], v38 offset:26144
	ds_read_b128 v[42:45], v50 offset:36352
	ds_read_b128 v[46:49], v50 offset:36384
	s_waitcnt lgkmcnt(1)
	v_mfma_f32_32x32x16_bf16 v[18:33], v[34:37], v[42:45], v[18:33]
	ds_read_b128 v[42:45], v50 offset:38912
	s_add_u32 s74, s74, 0x8000
	s_addc_u32 s75, s75, 0
	s_add_i32 s1, s1, 1
	s_cmp_lg_u32 s74, 0x400000
	s_waitcnt lgkmcnt(0)
	v_mfma_f32_32x32x16_bf16 v[2:17], v[34:37], v[42:45], v[2:17]
	ds_read_b128 v[34:37], v50 offset:38944
	v_add_u32_e32 v42, 0x2000, v108
	v_mfma_f32_32x32x16_bf16 v[18:33], v[38:41], v[46:49], v[18:33]
	s_waitcnt lgkmcnt(0)
	v_mfma_f32_32x32x16_bf16 v[2:17], v[38:41], v[34:37], v[2:17]
	s_nop 9
	v_cvt_pk_bf16_f32 v34, v18, v19
	v_cvt_pk_bf16_f32 v35, v20, v21
	v_cvt_pk_bf16_f32 v38, v22, v23
	v_cvt_pk_bf16_f32 v39, v24, v25
	ds_write2_b64 v108, v[34:35], v[38:39] offset1:2
	v_cvt_pk_bf16_f32 v34, v26, v27
	v_cvt_pk_bf16_f32 v35, v28, v29
	v_cvt_pk_bf16_f32 v36, v2, v3
	v_cvt_pk_bf16_f32 v37, v4, v5
	v_cvt_pk_bf16_f32 v40, v6, v7
	v_cvt_pk_bf16_f32 v41, v8, v9
	v_cvt_pk_bf16_f32 v38, v30, v31
	v_cvt_pk_bf16_f32 v39, v32, v33
	ds_write2_b64 v42, v[36:37], v[40:41] offset0:64 offset1:66
	v_cvt_pk_bf16_f32 v36, v10, v11
	v_cvt_pk_bf16_f32 v37, v12, v13
	v_cvt_pk_bf16_f32 v40, v14, v15
	v_cvt_pk_bf16_f32 v41, v16, v17
	ds_write2_b64 v108, v[34:35], v[38:39] offset0:4 offset1:6
	ds_write2_b64 v42, v[36:37], v[40:41] offset0:68 offset1:70
	s_waitcnt lgkmcnt(0)
	s_barrier
	s_cbranch_scc0 .LBB0_426

.Lmy_pc1:
	s_waitcnt vmcnt(0)
	v_cvt_pk_bf16_f32 v240, v224, v225
	v_cvt_pk_bf16_f32 v241, v226, v227
	v_cvt_pk_bf16_f32 v242, v228, v229
	v_cvt_pk_bf16_f32 v243, v230, v231
	global_store_dwordx2 v[234:235], v[240:241], off
	global_store_dwordx2 v[234:235], v[242:243], off offset:512
	v_lshl_add_u64 v[234:235], v[234:235], 0, s[100:101]
	s_cmpk_eq_i32 s1, 0x7f
	s_cbranch_scc1 .LBB0_421
	global_load_dwordx4 v[224:227], v[232:233], off
	global_load_dwordx4 v[228:231], v[232:233], off offset:1024
	v_lshl_add_u64 v[232:233], v[232:233], 0, s[98:99]
	s_branch .LBB0_421

	.amdhsa_kernel _Z10fwd_kernel6Params
		.amdhsa_group_segment_fixed_size 0
		.amdhsa_private_segment_fixed_size 0
		.amdhsa_kernarg_size 376
		.amdhsa_user_sgpr_count 2
		.amdhsa_user_sgpr_dispatch_ptr 0
		.amdhsa_user_sgpr_queue_ptr 0
		.amdhsa_user_sgpr_kernarg_segment_ptr 1
		.amdhsa_user_sgpr_dispatch_id 0
		.amdhsa_user_sgpr_kernarg_preload_length 0
		.amdhsa_user_sgpr_kernarg_preload_offset 0
		.amdhsa_user_sgpr_private_segment_size 0
		.amdhsa_uses_dynamic_stack 0
		.amdhsa_enable_private_segment 0
		.amdhsa_system_sgpr_workgroup_id_x 1
		.amdhsa_system_sgpr_workgroup_id_y 0
		.amdhsa_system_sgpr_workgroup_id_z 0
		.amdhsa_system_sgpr_workgroup_info 0
		.amdhsa_system_vgpr_workitem_id 0
		.amdhsa_next_free_vgpr 256
		.amdhsa_next_free_sgpr 102
		.amdhsa_accum_offset 256
		.amdhsa_reserve_vcc 1
		.amdhsa_float_round_mode_32 0
		.amdhsa_float_round_mode_16_64 0
		.amdhsa_float_denorm_mode_32 3
		.amdhsa_float_denorm_mode_16_64 3
		.amdhsa_dx10_clamp 1
		.amdhsa_ieee_mode 1
		.amdhsa_fp16_overflow 0
		.amdhsa_tg_split 0
		.amdhsa_exception_fp_ieee_invalid_op 0
		.amdhsa_exception_fp_denorm_src 0
		.amdhsa_exception_fp_ieee_div_zero 0
		.amdhsa_exception_fp_ieee_overflow 0
		.amdhsa_exception_fp_ieee_underflow 0
		.amdhsa_exception_fp_ieee_inexact 0
		.amdhsa_exception_int_div_zero 0
	.end_amdhsa_kernel

amdhsa.kernels:
  - .agpr_count:     0
    .args:
      - .offset:         0
        .size:           120
        .value_kind:     by_value
      - .offset:         120
        .size:           4
        .value_kind:     hidden_block_count_x
      - .offset:         124
        .size:           4
        .value_kind:     hidden_block_count_y
      - .offset:         128
        .size:           4
        .value_kind:     hidden_block_count_z
      - .offset:         132
        .size:           2
        .value_kind:     hidden_group_size_x
      - .offset:         134
        .size:           2
        .value_kind:     hidden_group_size_y
      - .offset:         136
        .size:           2
        .value_kind:     hidden_group_size_z
      - .offset:         138
        .size:           2
        .value_kind:     hidden_remainder_x
      - .offset:         140
        .size:           2
        .value_kind:     hidden_remainder_y
      - .offset:         142
        .size:           2
        .value_kind:     hidden_remainder_z
      - .offset:         160
        .size:           8
        .value_kind:     hidden_global_offset_x
      - .offset:         168
        .size:           8
        .value_kind:     hidden_global_offset_y
      - .offset:         176
        .size:           8
        .value_kind:     hidden_global_offset_z
      - .offset:         184
        .size:           2
        .value_kind:     hidden_grid_dims
      - .offset:         240
        .size:           4
        .value_kind:     hidden_dynamic_lds_size
    .group_segment_fixed_size: 0
    .kernarg_segment_align: 8
    .kernarg_segment_size: 376
    .language:       OpenCL C
    .language_version:
      - 2
      - 0
    .max_flat_workgroup_size: 512
    .name:           _Z10fwd_kernel6Params
    .private_segment_fixed_size: 0
    .sgpr_count:     108
    .sgpr_spill_count: 45
    .symbol:         _Z10fwd_kernel6Params.kd
    .uniform_work_group_size: 1
    .uses_dynamic_stack: false
    .vgpr_count:     256
    .vgpr_spill_count: 0
    .wavefront_size: 64
